# K-loops FFN-up/SSD-in/FFN-down: register-resident MFMAs issued first after the barrier, then LDS reads; LDS-DMA issues spread
# speedup vs baseline: 1.0237x; 1.0096x over previous
.LBB0_1161:
	s_and_b32 s21, s20, 0x18000
	v_add_u32_e32 v128, s21, v203
	s_add_i32 s21, s20, 0xfffe8000
	s_and_b32 s21, s21, 0x18000
	v_or_b32_e32 v222, s21, v202
	v_add_u32_e32 v223, s21, v199
	s_waitcnt vmcnt(8) lgkmcnt(0)
	s_barrier
	v_mfma_f32_32x32x16_bf16 v[112:127], v[150:153], v[142:145], v[112:127]
	v_mfma_f32_32x32x16_bf16 v[96:111], v[150:153], v[130:133], v[96:111]
	v_add_u32_e32 v180, v222, v200
	v_add_u32_e32 v224, v223, v200
	ds_read_b128 v[176:179], v180 offset:16384
	ds_read_b128 v[180:183], v180 offset:18432
	ds_read_b128 v[184:187], v224
	ds_read_b128 v[188:191], v224 offset:2048
	ds_read_b128 v[192:195], v224 offset:4096
	ds_read_b128 v[240:243], v224 offset:6144
	v_mfma_f32_32x32x16_bf16 v[80:95], v[146:149], v[142:145], v[80:95]
	v_mfma_f32_32x32x16_bf16 v[64:79], v[146:149], v[130:133], v[64:79]
	v_readfirstlane_b32 s21, v128
	s_mov_b32 m0, s21
	s_nop 0
	global_load_lds_dwordx4 v[172:173], off
	v_mfma_f32_32x32x16_bf16 v[48:63], v[138:141], v[142:145], v[48:63]
	v_mfma_f32_32x32x16_bf16 v[32:47], v[138:141], v[130:133], v[32:47]
	s_add_i32 s22, s21, 0x2000
	v_lshl_add_u64 v[150:151], v[172:173], 0, s[26:27]
	s_mov_b32 m0, s22
	s_nop 0
	global_load_lds_dwordx4 v[150:151], off
	v_mfma_f32_32x32x16_bf16 v[16:31], v[134:137], v[142:145], v[16:31]
	v_mfma_f32_32x32x16_bf16 v[0:15], v[134:137], v[130:133], v[0:15]
	v_add_u32_e32 v128, v222, v201
	ds_read_b128 v[142:145], v128 offset:16384
	ds_read_b128 v[130:133], v128 offset:18432
	v_add_u32_e32 v128, v223, v201
	ds_read_b128 v[150:153], v128
	ds_read_b128 v[146:149], v128 offset:2048
	ds_read_b128 v[138:141], v128 offset:4096
	ds_read_b128 v[134:137], v128 offset:6144
	s_waitcnt lgkmcnt(9)
	v_mfma_f32_32x32x16_bf16 v[112:127], v[184:187], v[176:179], v[112:127]
	s_add_i32 s22, s21, 0x6000
	s_addk_i32 s21, 0x4000
	v_mfma_f32_32x32x16_bf16 v[96:111], v[184:187], v[180:183], v[96:111]
	s_mov_b32 m0, s21
	s_nop 0
	global_load_lds_dwordx4 v[174:175], off
	v_lshl_add_u64 v[224:225], v[174:175], 0, s[26:27]
	s_waitcnt lgkmcnt(8)
	v_mfma_f32_32x32x16_bf16 v[80:95], v[188:191], v[176:179], v[80:95]
	v_mfma_f32_32x32x16_bf16 v[64:79], v[188:191], v[180:183], v[64:79]
	s_waitcnt lgkmcnt(7)
	v_mfma_f32_32x32x16_bf16 v[48:63], v[192:195], v[176:179], v[48:63]
	v_mfma_f32_32x32x16_bf16 v[32:47], v[192:195], v[180:183], v[32:47]
	s_mov_b32 m0, s22
	s_nop 0
	global_load_lds_dwordx4 v[224:225], off
	s_waitcnt lgkmcnt(6)
	v_mfma_f32_32x32x16_bf16 v[16:31], v[240:243], v[176:179], v[16:31]
	s_add_i32 s20, s20, 0x8000
	v_lshl_add_u64 v[172:173], v[172:173], 0, 64
	v_lshl_add_u64 v[174:175], v[174:175], 0, 64
	s_cmp_eq_u32 s20, 0x100000
	v_mfma_f32_32x32x16_bf16 v[0:15], v[240:243], v[180:183], v[0:15]
	s_cbranch_scc0 .LBB0_1161
	s_waitcnt vmcnt(8) lgkmcnt(0)
	s_barrier
	v_add_u32_e32 v128, v202, v200
	ds_read_b128 v[172:175], v128 offset:49152
	ds_read_b128 v[176:179], v128 offset:51200
	v_add_u32_e32 v128, v199, v200
	ds_read_b128 v[180:183], v128 offset:32768
	ds_read_b128 v[184:187], v128 offset:34816
	ds_read_b128 v[188:191], v128 offset:36864
	ds_read_b128 v[192:195], v128 offset:38912
	s_waitcnt lgkmcnt(9)
	v_mfma_f32_32x32x16_bf16 v[112:127], v[150:153], v[142:145], v[112:127]
	v_mfma_f32_32x32x16_bf16 v[96:111], v[150:153], v[130:133], v[96:111]
	s_waitcnt lgkmcnt(8)
	v_mfma_f32_32x32x16_bf16 v[80:95], v[146:149], v[142:145], v[80:95]
	v_mfma_f32_32x32x16_bf16 v[64:79], v[146:149], v[130:133], v[64:79]
	s_waitcnt lgkmcnt(7)
	v_mfma_f32_32x32x16_bf16 v[48:63], v[138:141], v[142:145], v[48:63]
	v_mfma_f32_32x32x16_bf16 v[32:47], v[138:141], v[130:133], v[32:47]
	s_waitcnt lgkmcnt(6)
	v_mfma_f32_32x32x16_bf16 v[16:31], v[134:137], v[142:145], v[16:31]
	v_mfma_f32_32x32x16_bf16 v[0:15], v[134:137], v[130:133], v[0:15]
	v_add_u32_e32 v128, v202, v201
	ds_read_b128 v[130:133], v128 offset:49152
	ds_read_b128 v[134:137], v128 offset:51200
	v_add_u32_e32 v128, v199, v201
	ds_read_b128 v[138:141], v128 offset:32768
	ds_read_b128 v[142:145], v128 offset:34816
	ds_read_b128 v[146:149], v128 offset:36864
	ds_read_b128 v[150:153], v128 offset:38912
	s_waitcnt lgkmcnt(9)
	v_mfma_f32_32x32x16_bf16 v[112:127], v[180:183], v[172:175], v[112:127]
	v_mfma_f32_32x32x16_bf16 v[96:111], v[180:183], v[176:179], v[96:111]
	s_waitcnt lgkmcnt(8)
	v_mfma_f32_32x32x16_bf16 v[80:95], v[184:187], v[172:175], v[80:95]
	v_mfma_f32_32x32x16_bf16 v[64:79], v[184:187], v[176:179], v[64:79]
	s_waitcnt lgkmcnt(7)
	v_mfma_f32_32x32x16_bf16 v[48:63], v[188:191], v[172:175], v[48:63]
	v_mfma_f32_32x32x16_bf16 v[32:47], v[188:191], v[176:179], v[32:47]
	s_waitcnt vmcnt(4) lgkmcnt(0)
	s_barrier
	v_add_u32_e32 v128, v236, v200
	s_waitcnt lgkmcnt(6)
	v_mfma_f32_32x32x16_bf16 v[16:31], v[192:195], v[172:175], v[16:31]
	v_mfma_f32_32x32x16_bf16 v[0:15], v[192:195], v[176:179], v[0:15]
	ds_read_b128 v[172:175], v128 offset:16384
	ds_read_b128 v[176:179], v128 offset:18432
	v_add_u32_e32 v128, v237, v200
	ds_read_b128 v[180:183], v128
	ds_read_b128 v[184:187], v128 offset:2048
	ds_read_b128 v[188:191], v128 offset:4096
	ds_read_b128 v[192:195], v128 offset:6144
	s_waitcnt lgkmcnt(9)
	v_mfma_f32_32x32x16_bf16 v[112:127], v[138:141], v[130:133], v[112:127]
	v_mfma_f32_32x32x16_bf16 v[96:111], v[138:141], v[134:137], v[96:111]
	s_waitcnt lgkmcnt(8)
	v_mfma_f32_32x32x16_bf16 v[80:95], v[142:145], v[130:133], v[80:95]
	v_mfma_f32_32x32x16_bf16 v[64:79], v[142:145], v[134:137], v[64:79]
	s_waitcnt lgkmcnt(7)
	v_mfma_f32_32x32x16_bf16 v[48:63], v[146:149], v[130:133], v[48:63]
	v_mfma_f32_32x32x16_bf16 v[32:47], v[146:149], v[134:137], v[32:47]
	s_waitcnt lgkmcnt(6)
	v_mfma_f32_32x32x16_bf16 v[16:31], v[150:153], v[130:133], v[16:31]
	v_mfma_f32_32x32x16_bf16 v[0:15], v[150:153], v[134:137], v[0:15]
	v_add_u32_e32 v128, v236, v201
	ds_read_b128 v[130:133], v128 offset:16384
	ds_read_b128 v[134:137], v128 offset:18432
	v_add_u32_e32 v128, v237, v201
	ds_read_b128 v[138:141], v128
	ds_read_b128 v[142:145], v128 offset:2048
	ds_read_b128 v[146:149], v128 offset:4096
	ds_read_b128 v[150:153], v128 offset:6144
	s_waitcnt lgkmcnt(9)
	v_mfma_f32_32x32x16_bf16 v[112:127], v[180:183], v[172:175], v[112:127]
	v_mfma_f32_32x32x16_bf16 v[96:111], v[180:183], v[176:179], v[96:111]
	s_waitcnt lgkmcnt(8)
	v_mfma_f32_32x32x16_bf16 v[80:95], v[184:187], v[172:175], v[80:95]
	v_mfma_f32_32x32x16_bf16 v[64:79], v[184:187], v[176:179], v[64:79]
	s_waitcnt lgkmcnt(7)
	v_mfma_f32_32x32x16_bf16 v[48:63], v[188:191], v[172:175], v[48:63]
	v_mfma_f32_32x32x16_bf16 v[32:47], v[188:191], v[176:179], v[32:47]
	s_waitcnt vmcnt(0) lgkmcnt(0)
	s_barrier
	v_add_u32_e32 v128, v234, v200
	s_waitcnt lgkmcnt(6)
	v_mfma_f32_32x32x16_bf16 v[16:31], v[192:195], v[172:175], v[16:31]
	v_mfma_f32_32x32x16_bf16 v[0:15], v[192:195], v[176:179], v[0:15]
	ds_read_b128 v[172:175], v128 offset:16384
	ds_read_b128 v[176:179], v128 offset:18432
	v_add_u32_e32 v128, v235, v200
	ds_read_b128 v[180:183], v128
	ds_read_b128 v[184:187], v128 offset:2048
	ds_read_b128 v[188:191], v128 offset:4096
	ds_read_b128 v[192:195], v128 offset:6144
	s_waitcnt lgkmcnt(9)
	v_mfma_f32_32x32x16_bf16 v[112:127], v[138:141], v[130:133], v[112:127]
	v_mfma_f32_32x32x16_bf16 v[96:111], v[138:141], v[134:137], v[96:111]
	s_waitcnt lgkmcnt(8)
	v_mfma_f32_32x32x16_bf16 v[80:95], v[142:145], v[130:133], v[80:95]
	v_mfma_f32_32x32x16_bf16 v[64:79], v[142:145], v[134:137], v[64:79]
	s_waitcnt lgkmcnt(7)
	v_mfma_f32_32x32x16_bf16 v[48:63], v[146:149], v[130:133], v[48:63]
	v_mfma_f32_32x32x16_bf16 v[32:47], v[146:149], v[134:137], v[32:47]
	s_waitcnt lgkmcnt(6)
	v_mfma_f32_32x32x16_bf16 v[16:31], v[150:153], v[130:133], v[16:31]
	v_mfma_f32_32x32x16_bf16 v[0:15], v[150:153], v[134:137], v[0:15]
	v_add_u32_e32 v128, v234, v201
	ds_read_b128 v[130:133], v128 offset:16384
	ds_read_b128 v[136:139], v128 offset:18432
	v_add_u32_e32 v128, v235, v201
	ds_read_b128 v[140:143], v128
	ds_read_b128 v[144:147], v128 offset:2048
	ds_read_b128 v[148:151], v128 offset:4096
	ds_read_b128 v[240:243], v128 offset:6144
	s_waitcnt lgkmcnt(9)
	v_mfma_f32_32x32x16_bf16 v[112:127], v[180:183], v[172:175], v[112:127]
	v_mfma_f32_32x32x16_bf16 v[96:111], v[180:183], v[176:179], v[96:111]
	s_waitcnt lgkmcnt(8)
	v_mfma_f32_32x32x16_bf16 v[80:95], v[184:187], v[172:175], v[80:95]
	v_mfma_f32_32x32x16_bf16 v[64:79], v[184:187], v[176:179], v[64:79]
	s_waitcnt lgkmcnt(7)
	v_mfma_f32_32x32x16_bf16 v[48:63], v[188:191], v[172:175], v[48:63]
	v_mfma_f32_32x32x16_bf16 v[32:47], v[188:191], v[176:179], v[32:47]
	s_waitcnt lgkmcnt(6)
	v_mfma_f32_32x32x16_bf16 v[16:31], v[192:195], v[172:175], v[16:31]
	v_or_b32_e32 v134, s1, v196
	s_movk_i32 s1, 0x1840
	v_cmp_gt_i32_e32 vcc, s1, v134
	v_mfma_f32_32x32x16_bf16 v[0:15], v[192:195], v[176:179], v[0:15]
	s_waitcnt lgkmcnt(3)
	v_mfma_f32_32x32x16_bf16 v[112:127], v[140:143], v[130:133], v[112:127]
	v_mfma_f32_32x32x16_bf16 v[96:111], v[140:143], v[136:139], v[96:111]
	s_waitcnt lgkmcnt(2)
	v_mfma_f32_32x32x16_bf16 v[80:95], v[144:147], v[130:133], v[80:95]
	v_mfma_f32_32x32x16_bf16 v[64:79], v[144:147], v[136:139], v[64:79]
	s_waitcnt lgkmcnt(1)
	v_mfma_f32_32x32x16_bf16 v[48:63], v[148:151], v[130:133], v[48:63]
	v_mfma_f32_32x32x16_bf16 v[32:47], v[148:151], v[136:139], v[32:47]
	s_waitcnt lgkmcnt(0)
	v_mfma_f32_32x32x16_bf16 v[16:31], v[240:243], v[130:133], v[16:31]
	v_mfma_f32_32x32x16_bf16 v[0:15], v[240:243], v[136:139], v[0:15]
	s_and_saveexec_b64 s[20:21], vcc
	s_cbranch_execz .LBB0_1159
	v_add_u32_e32 v239, s0, v159
	s_movk_i32 s0, 0x7ff
	v_cmp_lt_i32_e32 vcc, s0, v134
	s_and_saveexec_b64 s[0:1], vcc
	s_xor_b64 s[22:23], exec, s[0:1]
	s_cbranch_execz .LBB0_1816
	s_cmpk_lt_u32 s24, 0x1800
	v_or_b32_e32 v130, v134, v197
	s_mov_b64 s[0:1], -1
	s_cbranch_scc0 .LBB0_1302
	v_add_u32_e32 v128, 0xfffff800, v130
	v_lshlrev_b64 v[132:133], 2, v[128:129]
	v_lshl_add_u64 v[134:135], s[16:17], 0, v[132:133]
	v_add_co_u32_e32 v136, vcc, 0x4000, v134
	v_lshl_add_u64 v[132:133], s[18:19], 0, v[132:133]
	s_nop 0
	v_addc_co_u32_e32 v137, vcc, 0, v135, vcc
	v_add_co_u32_e32 v138, vcc, 0x8000, v134
	v_mov_b32_e32 v131, v113
	s_nop 0
	v_addc_co_u32_e32 v139, vcc, 0, v135, vcc
	global_load_dword v188, v[134:135], off
	s_nop 0
	global_load_dword v134, v[136:137], off
	global_load_dword v186, v[138:139], off
	global_load_dword v190, v[132:133], off
	v_ashrrev_i32_e32 v132, 7, v239
	v_ashrrev_i32_e32 v133, 31, v132
	v_lshlrev_b64 v[136:137], 15, v[132:133]
	v_lshl_add_u64 v[178:179], s[2:3], 0, v[136:137]
	v_lshl_add_u64 v[136:137], v[128:129], 1, v[178:179]
	s_and_saveexec_b64 s[0:1], s[6:7]
	s_xor_b64 s[0:1], exec, s[0:1]
	s_cbranch_execz .LBB0_1167
	v_add_co_u32_e32 v138, vcc, 0x4000, v136
	v_cvt_pk_bf16_f32 v131, v30, s0
	s_nop 0
	v_addc_co_u32_e32 v139, vcc, 0, v137, vcc
	global_store_short v[138:139], v131, off
	v_mov_b32_e32 v131, v31

.LBB0_2340:
	s_and_b32 s19, s18, 0x18000
	v_add_u32_e32 v187, s19, v180
	s_add_i32 s19, s18, 0xfffe8000
	s_and_b32 s19, s19, 0x18000
	v_or_b32_e32 v212, s19, v179
	v_add_u32_e32 v213, s19, v176
	s_waitcnt vmcnt(8) lgkmcnt(0)
	s_barrier
	v_mfma_f32_32x32x16_bf16 v[112:127], v[150:153], v[142:145], v[112:127]
	v_mfma_f32_32x32x16_bf16 v[96:111], v[150:153], v[130:133], v[96:111]
	v_add_u32_e32 v192, v212, v177
	v_add_u32_e32 v208, v213, v177
	ds_read_b128 v[188:191], v192 offset:16384
	ds_read_b128 v[192:195], v192 offset:18432
	ds_read_b128 v[196:199], v208
	ds_read_b128 v[200:203], v208 offset:2048
	ds_read_b128 v[204:207], v208 offset:4096
	ds_read_b128 v[208:211], v208 offset:6144
	v_mfma_f32_32x32x16_bf16 v[80:95], v[146:149], v[142:145], v[80:95]
	v_mfma_f32_32x32x16_bf16 v[64:79], v[146:149], v[130:133], v[64:79]
	v_readfirstlane_b32 s19, v187
	s_mov_b32 m0, s19
	s_nop 0
	global_load_lds_dwordx4 v[170:171], off
	v_mfma_f32_32x32x16_bf16 v[48:63], v[138:141], v[142:145], v[48:63]
	v_mfma_f32_32x32x16_bf16 v[32:47], v[138:141], v[130:133], v[32:47]
	s_add_i32 s20, s19, 0x2000
	v_lshl_add_u64 v[150:151], v[170:171], 0, s[34:35]
	s_mov_b32 m0, s20
	s_nop 0
	global_load_lds_dwordx4 v[150:151], off
	v_mfma_f32_32x32x16_bf16 v[16:31], v[134:137], v[142:145], v[16:31]
	v_mfma_f32_32x32x16_bf16 v[0:15], v[134:137], v[130:133], v[0:15]
	v_add_u32_e32 v130, v212, v178
	v_add_u32_e32 v134, v213, v178
	ds_read_b128 v[142:145], v130 offset:16384
	ds_read_b128 v[130:133], v130 offset:18432
	ds_read_b128 v[150:153], v134
	ds_read_b128 v[146:149], v134 offset:2048
	ds_read_b128 v[138:141], v134 offset:4096
	ds_read_b128 v[134:137], v134 offset:6144
	s_waitcnt lgkmcnt(9)
	v_mfma_f32_32x32x16_bf16 v[112:127], v[196:199], v[188:191], v[112:127]
	s_add_i32 s20, s19, 0x6000
	s_addk_i32 s19, 0x4000
	v_mfma_f32_32x32x16_bf16 v[96:111], v[196:199], v[192:195], v[96:111]
	s_mov_b32 m0, s19
	s_nop 0
	global_load_lds_dwordx4 v[172:173], off
	v_lshl_add_u64 v[212:213], v[172:173], 0, s[34:35]
	s_waitcnt lgkmcnt(8)
	v_mfma_f32_32x32x16_bf16 v[80:95], v[200:203], v[188:191], v[80:95]
	v_mfma_f32_32x32x16_bf16 v[64:79], v[200:203], v[192:195], v[64:79]
	s_waitcnt lgkmcnt(7)
	v_mfma_f32_32x32x16_bf16 v[48:63], v[204:207], v[188:191], v[48:63]
	v_mfma_f32_32x32x16_bf16 v[32:47], v[204:207], v[192:195], v[32:47]
	s_mov_b32 m0, s20
	s_nop 0
	global_load_lds_dwordx4 v[212:213], off
	s_waitcnt lgkmcnt(6)
	v_mfma_f32_32x32x16_bf16 v[16:31], v[208:211], v[188:191], v[16:31]
	s_add_i32 s18, s18, 0x8000
	v_lshl_add_u64 v[170:171], v[170:171], 0, 64
	v_lshl_add_u64 v[172:173], v[172:173], 0, 64
	s_cmp_eq_u32 s18, 0x100000
	v_mfma_f32_32x32x16_bf16 v[0:15], v[208:211], v[192:195], v[0:15]
	s_cbranch_scc0 .LBB0_2340
	s_waitcnt vmcnt(8) lgkmcnt(0)
	s_barrier
	v_add_u32_e32 v187, v179, v177
	ds_read_b128 v[170:173], v187 offset:49152
	ds_read_b128 v[188:191], v187 offset:51200
	v_add_u32_e32 v187, v176, v177
	ds_read_b128 v[192:195], v187 offset:32768
	ds_read_b128 v[196:199], v187 offset:34816
	ds_read_b128 v[200:203], v187 offset:36864
	ds_read_b128 v[204:207], v187 offset:38912
	s_waitcnt lgkmcnt(9)
	v_mfma_f32_32x32x16_bf16 v[112:127], v[150:153], v[142:145], v[112:127]
	v_mfma_f32_32x32x16_bf16 v[96:111], v[150:153], v[130:133], v[96:111]
	s_waitcnt lgkmcnt(8)
	v_mfma_f32_32x32x16_bf16 v[80:95], v[146:149], v[142:145], v[80:95]
	v_mfma_f32_32x32x16_bf16 v[64:79], v[146:149], v[130:133], v[64:79]
	s_waitcnt lgkmcnt(7)
	v_mfma_f32_32x32x16_bf16 v[48:63], v[138:141], v[142:145], v[48:63]
	v_mfma_f32_32x32x16_bf16 v[32:47], v[138:141], v[130:133], v[32:47]
	s_waitcnt lgkmcnt(6)
	v_mfma_f32_32x32x16_bf16 v[16:31], v[134:137], v[142:145], v[16:31]
	v_mfma_f32_32x32x16_bf16 v[0:15], v[134:137], v[130:133], v[0:15]
	v_add_u32_e32 v134, v179, v178
	v_add_u32_e32 v150, v176, v178
	ds_read_b128 v[130:133], v134 offset:49152
	ds_read_b128 v[134:137], v134 offset:51200
	ds_read_b128 v[138:141], v150 offset:32768
	ds_read_b128 v[142:145], v150 offset:34816
	ds_read_b128 v[146:149], v150 offset:36864
	ds_read_b128 v[150:153], v150 offset:38912
	s_waitcnt lgkmcnt(9)
	v_mfma_f32_32x32x16_bf16 v[112:127], v[192:195], v[170:173], v[112:127]
	v_mfma_f32_32x32x16_bf16 v[96:111], v[192:195], v[188:191], v[96:111]
	s_waitcnt lgkmcnt(8)
	v_mfma_f32_32x32x16_bf16 v[80:95], v[196:199], v[170:173], v[80:95]
	v_mfma_f32_32x32x16_bf16 v[64:79], v[196:199], v[188:191], v[64:79]
	s_waitcnt lgkmcnt(7)
	v_mfma_f32_32x32x16_bf16 v[48:63], v[200:203], v[170:173], v[48:63]
	v_mfma_f32_32x32x16_bf16 v[32:47], v[200:203], v[188:191], v[32:47]
	s_waitcnt vmcnt(4) lgkmcnt(0)
	s_barrier
	v_add_u32_e32 v187, v184, v177
	s_waitcnt lgkmcnt(6)
	v_mfma_f32_32x32x16_bf16 v[16:31], v[204:207], v[170:173], v[16:31]
	v_mfma_f32_32x32x16_bf16 v[0:15], v[204:207], v[188:191], v[0:15]
	ds_read_b128 v[170:173], v187 offset:16384
	ds_read_b128 v[188:191], v187 offset:18432
	v_add_u32_e32 v187, v185, v177
	ds_read_b128 v[192:195], v187
	ds_read_b128 v[196:199], v187 offset:2048
	ds_read_b128 v[200:203], v187 offset:4096
	ds_read_b128 v[204:207], v187 offset:6144
	s_waitcnt lgkmcnt(9)
	v_mfma_f32_32x32x16_bf16 v[112:127], v[138:141], v[130:133], v[112:127]
	v_mfma_f32_32x32x16_bf16 v[96:111], v[138:141], v[134:137], v[96:111]
	s_waitcnt lgkmcnt(8)
	v_mfma_f32_32x32x16_bf16 v[80:95], v[142:145], v[130:133], v[80:95]
	v_mfma_f32_32x32x16_bf16 v[64:79], v[142:145], v[134:137], v[64:79]
	s_waitcnt lgkmcnt(7)
	v_mfma_f32_32x32x16_bf16 v[48:63], v[146:149], v[130:133], v[48:63]
	v_mfma_f32_32x32x16_bf16 v[32:47], v[146:149], v[134:137], v[32:47]
	s_waitcnt lgkmcnt(6)
	v_mfma_f32_32x32x16_bf16 v[16:31], v[150:153], v[130:133], v[16:31]
	v_mfma_f32_32x32x16_bf16 v[0:15], v[150:153], v[134:137], v[0:15]
	v_add_u32_e32 v134, v184, v178
	v_add_u32_e32 v150, v185, v178
	ds_read_b128 v[130:133], v134 offset:16384
	ds_read_b128 v[134:137], v134 offset:18432
	ds_read_b128 v[138:141], v150
	ds_read_b128 v[142:145], v150 offset:2048
	ds_read_b128 v[146:149], v150 offset:4096
	ds_read_b128 v[150:153], v150 offset:6144
	s_waitcnt lgkmcnt(9)
	v_mfma_f32_32x32x16_bf16 v[112:127], v[192:195], v[170:173], v[112:127]
	v_mfma_f32_32x32x16_bf16 v[96:111], v[192:195], v[188:191], v[96:111]
	s_waitcnt lgkmcnt(8)
	v_mfma_f32_32x32x16_bf16 v[80:95], v[196:199], v[170:173], v[80:95]
	v_mfma_f32_32x32x16_bf16 v[64:79], v[196:199], v[188:191], v[64:79]
	s_waitcnt lgkmcnt(7)
	v_mfma_f32_32x32x16_bf16 v[48:63], v[200:203], v[170:173], v[48:63]
	v_mfma_f32_32x32x16_bf16 v[32:47], v[200:203], v[188:191], v[32:47]
	s_waitcnt vmcnt(0) lgkmcnt(0)
	s_barrier
	v_add_u32_e32 v187, v182, v177
	s_waitcnt lgkmcnt(6)
	v_mfma_f32_32x32x16_bf16 v[16:31], v[204:207], v[170:173], v[16:31]
	v_mfma_f32_32x32x16_bf16 v[0:15], v[204:207], v[188:191], v[0:15]
	ds_read_b128 v[170:173], v187 offset:16384
	ds_read_b128 v[188:191], v187 offset:18432
	v_add_u32_e32 v187, v183, v177
	ds_read_b128 v[192:195], v187
	ds_read_b128 v[196:199], v187 offset:2048
	ds_read_b128 v[200:203], v187 offset:4096
	ds_read_b128 v[204:207], v187 offset:6144
	s_waitcnt lgkmcnt(9)
	v_mfma_f32_32x32x16_bf16 v[112:127], v[138:141], v[130:133], v[112:127]
	v_mfma_f32_32x32x16_bf16 v[96:111], v[138:141], v[134:137], v[96:111]
	s_waitcnt lgkmcnt(8)
	v_mfma_f32_32x32x16_bf16 v[80:95], v[142:145], v[130:133], v[80:95]
	v_mfma_f32_32x32x16_bf16 v[64:79], v[142:145], v[134:137], v[64:79]
	s_waitcnt lgkmcnt(7)
	v_mfma_f32_32x32x16_bf16 v[48:63], v[146:149], v[130:133], v[48:63]
	v_mfma_f32_32x32x16_bf16 v[32:47], v[146:149], v[134:137], v[32:47]
	s_waitcnt lgkmcnt(6)
	v_mfma_f32_32x32x16_bf16 v[16:31], v[150:153], v[130:133], v[16:31]
	v_mfma_f32_32x32x16_bf16 v[0:15], v[150:153], v[134:137], v[0:15]
	v_add_u32_e32 v134, v182, v178
	v_add_u32_e32 v150, v183, v178
	ds_read_b128 v[130:133], v134 offset:16384
	ds_read_b128 v[134:137], v134 offset:18432
	ds_read_b128 v[138:141], v150
	ds_read_b128 v[142:145], v150 offset:2048
	ds_read_b128 v[146:149], v150 offset:4096
	ds_read_b128 v[150:153], v150 offset:6144
	s_waitcnt lgkmcnt(9)
	v_mfma_f32_32x32x16_bf16 v[112:127], v[192:195], v[170:173], v[112:127]
	v_mfma_f32_32x32x16_bf16 v[96:111], v[192:195], v[188:191], v[96:111]
	s_waitcnt lgkmcnt(8)
	v_mfma_f32_32x32x16_bf16 v[80:95], v[196:199], v[170:173], v[80:95]
	v_mfma_f32_32x32x16_bf16 v[64:79], v[196:199], v[188:191], v[64:79]
	s_waitcnt lgkmcnt(7)
	v_mfma_f32_32x32x16_bf16 v[48:63], v[200:203], v[170:173], v[48:63]
	v_mfma_f32_32x32x16_bf16 v[32:47], v[200:203], v[188:191], v[32:47]
	s_waitcnt lgkmcnt(6)
	v_mfma_f32_32x32x16_bf16 v[16:31], v[204:207], v[170:173], v[16:31]
	v_mfma_f32_32x32x16_bf16 v[0:15], v[204:207], v[188:191], v[0:15]
	s_waitcnt lgkmcnt(3)
	v_mfma_f32_32x32x16_bf16 v[112:127], v[138:141], v[130:133], v[112:127]
	s_waitcnt lgkmcnt(2)
	v_mfma_f32_32x32x16_bf16 v[80:95], v[142:145], v[130:133], v[80:95]
	s_waitcnt lgkmcnt(1)
	v_mfma_f32_32x32x16_bf16 v[48:63], v[146:149], v[130:133], v[48:63]
	s_waitcnt lgkmcnt(0)
	v_mfma_f32_32x32x16_bf16 v[16:31], v[150:153], v[130:133], v[16:31]
	v_or_b32_e32 v132, s12, v174
	v_ashrrev_i32_e32 v130, 1, v132
	v_or_b32_e32 v130, v130, v154
	v_ashrrev_i32_e32 v131, 31, v130
	s_movk_i32 s12, 0x5000
	v_mfma_f32_32x32x16_bf16 v[96:111], v[138:141], v[134:137], v[96:111]
	v_mfma_f32_32x32x16_bf16 v[64:79], v[142:145], v[134:137], v[64:79]
	v_add_u32_e32 v142, s13, v155
	s_mov_b32 s13, 0xb000
	v_ashrrev_i32_e32 v133, 7, v142
	v_mfma_f32_32x32x16_bf16 v[32:47], v[146:149], v[134:137], v[32:47]
	v_mfma_f32_32x32x16_bf16 v[0:15], v[150:153], v[134:137], v[0:15]
	v_lshl_add_u64 v[134:135], v[130:131], 2, s[10:11]
	v_add_co_u32_e32 v138, vcc, s12, v134
	s_mov_b32 s12, 0x8000
	s_nop 0
	v_addc_co_u32_e32 v139, vcc, 0, v135, vcc
	global_load_dword v137, v[138:139], off offset:2048
	v_add_co_u32_e32 v138, vcc, s13, v134
	global_load_dword v136, v[134:135], off
	s_nop 0
	v_addc_co_u32_e32 v139, vcc, 0, v135, vcc
	v_add_co_u32_e32 v140, vcc, s47, v134
	global_load_dword v139, v[138:139], off
	s_nop 0
	v_addc_co_u32_e32 v141, vcc, 0, v135, vcc
	global_load_dword v138, v[140:141], off offset:3072
	v_add_co_u32_e32 v140, vcc, s12, v134
	s_mov_b32 s12, 0xd000
	s_nop 0
	v_addc_co_u32_e32 v141, vcc, 0, v135, vcc
	v_add_co_u32_e32 v134, vcc, s12, v134
	global_load_dword v140, v[140:141], off offset:1024
	s_nop 0
	v_addc_co_u32_e32 v135, vcc, 0, v135, vcc
	global_load_dword v141, v[134:135], off offset:3072
	v_mov_b64_e32 v[134:135], s[8:9]
	v_mad_i64_i32 v[134:135], s[12:13], v133, s13, v[134:135]
	v_ashrrev_i32_e32 v133, 31, v132
	v_lshl_add_u64 v[132:133], v[132:133], 1, v[134:135]
	v_lshl_add_u64 v[132:133], v[132:133], 0, v[128:129]
	s_and_saveexec_b64 s[12:13], s[2:3]
	s_xor_b64 s[12:13], exec, s[12:13]
	s_cbranch_execz .LBB0_2343
	v_add_co_u32_e32 v134, vcc, 0x5000, v132
	v_cvt_pk_bf16_f32 v143, v30, s0
	s_nop 0
	v_addc_co_u32_e32 v135, vcc, 0, v133, vcc
	global_store_short v[134:135], v143, off offset:2048
	v_cvt_pk_bf16_f32 v143, v14, s0
	global_store_short v[134:135], v143, off offset:2112
	v_add_co_u32_e32 v134, vcc, 0x8000, v132
	v_cvt_pk_bf16_f32 v143, v31, s0
	s_nop 0
	v_addc_co_u32_e32 v135, vcc, 0, v133, vcc
	global_store_short v[134:135], v143, off offset:1024

.LBB0_2551:
	s_and_b32 s7, s5, 0x18000
	v_add_u32_e32 v222, s7, v180
	s_add_i32 s7, s5, 0xfffe8000
	s_and_b32 s7, s7, 0x18000
	v_or_b32_e32 v223, s7, v179
	v_add_u32_e32 v233, s7, v176
	s_waitcnt vmcnt(8) lgkmcnt(0)
	s_barrier
	v_mfma_f32_32x32x16_bf16 v[112:127], v[150:153], v[142:145], v[112:127]
	v_mfma_f32_32x32x16_bf16 v[96:111], v[150:153], v[130:133], v[96:111]
	v_add_u32_e32 v206, v223, v177
	v_add_u32_e32 v234, v233, v177
	ds_read_b128 v[202:205], v206 offset:16384
	ds_read_b128 v[206:209], v206 offset:18432
	ds_read_b128 v[210:213], v234
	ds_read_b128 v[214:217], v234 offset:2048
	ds_read_b128 v[224:227], v234 offset:4096
	ds_read_b128 v[234:237], v234 offset:6144
	v_mfma_f32_32x32x16_bf16 v[80:95], v[146:149], v[142:145], v[80:95]
	v_mfma_f32_32x32x16_bf16 v[64:79], v[146:149], v[130:133], v[64:79]
	v_readfirstlane_b32 s7, v222
	s_mov_b32 m0, s7
	s_nop 0
	global_load_lds_dwordx4 v[170:171], off
	v_mfma_f32_32x32x16_bf16 v[48:63], v[138:141], v[142:145], v[48:63]
	v_mfma_f32_32x32x16_bf16 v[32:47], v[138:141], v[130:133], v[32:47]
	s_add_i32 s8, s7, 0x2000
	v_lshl_add_u64 v[150:151], v[170:171], 0, s[10:11]
	s_mov_b32 m0, s8
	s_nop 0
	global_load_lds_dwordx4 v[150:151], off
	v_mfma_f32_32x32x16_bf16 v[16:31], v[134:137], v[142:145], v[16:31]
	v_mfma_f32_32x32x16_bf16 v[0:15], v[134:137], v[130:133], v[0:15]
	v_add_u32_e32 v130, v223, v178
	v_add_u32_e32 v134, v233, v178
	ds_read_b128 v[142:145], v130 offset:16384
	ds_read_b128 v[130:133], v130 offset:18432
	ds_read_b128 v[150:153], v134
	ds_read_b128 v[146:149], v134 offset:2048
	ds_read_b128 v[138:141], v134 offset:4096
	ds_read_b128 v[134:137], v134 offset:6144
	s_waitcnt lgkmcnt(9)
	v_mfma_f32_32x32x16_bf16 v[112:127], v[210:213], v[202:205], v[112:127]
	s_add_i32 s8, s7, 0x6000
	s_addk_i32 s7, 0x4000
	v_mfma_f32_32x32x16_bf16 v[96:111], v[210:213], v[206:209], v[96:111]
	s_mov_b32 m0, s7
	s_nop 0
	global_load_lds_dwordx4 v[172:173], off
	v_lshl_add_u64 v[222:223], v[172:173], 0, s[10:11]
	s_waitcnt lgkmcnt(8)
	v_mfma_f32_32x32x16_bf16 v[80:95], v[214:217], v[202:205], v[80:95]
	v_mfma_f32_32x32x16_bf16 v[64:79], v[214:217], v[206:209], v[64:79]
	s_waitcnt lgkmcnt(7)
	v_mfma_f32_32x32x16_bf16 v[48:63], v[224:227], v[202:205], v[48:63]
	v_mfma_f32_32x32x16_bf16 v[32:47], v[224:227], v[206:209], v[32:47]
	s_mov_b32 m0, s8
	s_nop 0
	global_load_lds_dwordx4 v[222:223], off
	s_waitcnt lgkmcnt(6)
	v_mfma_f32_32x32x16_bf16 v[16:31], v[234:237], v[202:205], v[16:31]
	s_add_i32 s5, s5, 0x8000
	v_lshl_add_u64 v[170:171], v[170:171], 0, 64
	v_lshl_add_u64 v[172:173], v[172:173], 0, 64
	s_cmp_eq_u32 s5, 0x2c0000
	v_mfma_f32_32x32x16_bf16 v[0:15], v[234:237], v[206:209], v[0:15]
	s_cbranch_scc0 .LBB0_2551
	s_waitcnt vmcnt(8) lgkmcnt(0)
	s_barrier
	v_add_u32_e32 v202, v179, v177
	v_add_u32_e32 v222, v176, v177
	ds_read_b128 v[170:173], v202 offset:49152
	ds_read_b128 v[202:205], v202 offset:51200
	ds_read_b128 v[206:209], v222 offset:32768
	ds_read_b128 v[210:213], v222 offset:34816
	ds_read_b128 v[214:217], v222 offset:36864
	ds_read_b128 v[224:227], v222 offset:38912
	s_waitcnt lgkmcnt(9)
	v_mfma_f32_32x32x16_bf16 v[112:127], v[150:153], v[142:145], v[112:127]
	v_mfma_f32_32x32x16_bf16 v[96:111], v[150:153], v[130:133], v[96:111]
	s_waitcnt lgkmcnt(8)
	v_mfma_f32_32x32x16_bf16 v[80:95], v[146:149], v[142:145], v[80:95]
	v_mfma_f32_32x32x16_bf16 v[64:79], v[146:149], v[130:133], v[64:79]
	s_waitcnt lgkmcnt(7)
	v_mfma_f32_32x32x16_bf16 v[48:63], v[138:141], v[142:145], v[48:63]
	v_mfma_f32_32x32x16_bf16 v[32:47], v[138:141], v[130:133], v[32:47]
	s_waitcnt lgkmcnt(6)
	v_mfma_f32_32x32x16_bf16 v[16:31], v[134:137], v[142:145], v[16:31]
	v_mfma_f32_32x32x16_bf16 v[0:15], v[134:137], v[130:133], v[0:15]
	v_add_u32_e32 v134, v179, v178
	v_add_u32_e32 v150, v176, v178
	ds_read_b128 v[130:133], v134 offset:49152
	ds_read_b128 v[134:137], v134 offset:51200
	ds_read_b128 v[138:141], v150 offset:32768
	ds_read_b128 v[142:145], v150 offset:34816
	ds_read_b128 v[146:149], v150 offset:36864
	ds_read_b128 v[150:153], v150 offset:38912
	s_waitcnt lgkmcnt(9)
	v_mfma_f32_32x32x16_bf16 v[112:127], v[206:209], v[170:173], v[112:127]
	v_mfma_f32_32x32x16_bf16 v[96:111], v[206:209], v[202:205], v[96:111]
	s_waitcnt lgkmcnt(8)
	v_mfma_f32_32x32x16_bf16 v[80:95], v[210:213], v[170:173], v[80:95]
	v_mfma_f32_32x32x16_bf16 v[64:79], v[210:213], v[202:205], v[64:79]
	s_waitcnt lgkmcnt(7)
	v_mfma_f32_32x32x16_bf16 v[48:63], v[214:217], v[170:173], v[48:63]
	v_mfma_f32_32x32x16_bf16 v[32:47], v[214:217], v[202:205], v[32:47]
	s_waitcnt lgkmcnt(6)
	v_mfma_f32_32x32x16_bf16 v[0:15], v[224:227], v[202:205], v[0:15]
	s_waitcnt vmcnt(4) lgkmcnt(0)
	s_barrier
	v_add_u32_e32 v202, v199, v177
	v_add_u32_e32 v222, v200, v177
	v_mfma_f32_32x32x16_bf16 v[16:31], v[224:227], v[170:173], v[16:31]
	ds_read_b128 v[170:173], v202 offset:16384
	ds_read_b128 v[202:205], v202 offset:18432
	ds_read_b128 v[206:209], v222
	ds_read_b128 v[210:213], v222 offset:2048
	ds_read_b128 v[214:217], v222 offset:4096
	ds_read_b128 v[224:227], v222 offset:6144
	s_waitcnt lgkmcnt(9)
	v_mfma_f32_32x32x16_bf16 v[112:127], v[138:141], v[130:133], v[112:127]
	v_mfma_f32_32x32x16_bf16 v[96:111], v[138:141], v[134:137], v[96:111]
	s_waitcnt lgkmcnt(8)
	v_mfma_f32_32x32x16_bf16 v[80:95], v[142:145], v[130:133], v[80:95]
	v_mfma_f32_32x32x16_bf16 v[64:79], v[142:145], v[134:137], v[64:79]
	s_waitcnt lgkmcnt(7)
	v_mfma_f32_32x32x16_bf16 v[48:63], v[146:149], v[130:133], v[48:63]
	v_mfma_f32_32x32x16_bf16 v[32:47], v[146:149], v[134:137], v[32:47]
	s_waitcnt lgkmcnt(6)
	v_mfma_f32_32x32x16_bf16 v[16:31], v[150:153], v[130:133], v[16:31]
	v_mfma_f32_32x32x16_bf16 v[0:15], v[150:153], v[134:137], v[0:15]
	v_add_u32_e32 v134, v199, v178
	v_add_u32_e32 v150, v200, v178
	ds_read_b128 v[130:133], v134 offset:16384
	ds_read_b128 v[134:137], v134 offset:18432
	ds_read_b128 v[138:141], v150
	ds_read_b128 v[142:145], v150 offset:2048
	ds_read_b128 v[146:149], v150 offset:4096
	ds_read_b128 v[150:153], v150 offset:6144
	s_waitcnt lgkmcnt(9)
	v_mfma_f32_32x32x16_bf16 v[112:127], v[206:209], v[170:173], v[112:127]
	v_mfma_f32_32x32x16_bf16 v[96:111], v[206:209], v[202:205], v[96:111]
	s_waitcnt lgkmcnt(8)
	v_mfma_f32_32x32x16_bf16 v[80:95], v[210:213], v[170:173], v[80:95]
	v_mfma_f32_32x32x16_bf16 v[64:79], v[210:213], v[202:205], v[64:79]
	s_waitcnt lgkmcnt(7)
	v_mfma_f32_32x32x16_bf16 v[48:63], v[214:217], v[170:173], v[48:63]
	v_mfma_f32_32x32x16_bf16 v[32:47], v[214:217], v[202:205], v[32:47]
	s_waitcnt lgkmcnt(6)
	v_mfma_f32_32x32x16_bf16 v[0:15], v[224:227], v[202:205], v[0:15]
	s_waitcnt vmcnt(0) lgkmcnt(0)
	s_barrier
	v_add_u32_e32 v202, v197, v177
	v_add_u32_e32 v222, v198, v177
	v_mfma_f32_32x32x16_bf16 v[16:31], v[224:227], v[170:173], v[16:31]
	ds_read_b128 v[170:173], v202 offset:16384
	ds_read_b128 v[202:205], v202 offset:18432
	ds_read_b128 v[206:209], v222
	ds_read_b128 v[210:213], v222 offset:2048
	ds_read_b128 v[214:217], v222 offset:4096
	ds_read_b128 v[224:227], v222 offset:6144
	s_waitcnt lgkmcnt(9)
	v_mfma_f32_32x32x16_bf16 v[112:127], v[138:141], v[130:133], v[112:127]
	v_mfma_f32_32x32x16_bf16 v[96:111], v[138:141], v[134:137], v[96:111]
	s_waitcnt lgkmcnt(8)
	v_mfma_f32_32x32x16_bf16 v[80:95], v[142:145], v[130:133], v[80:95]
	v_mfma_f32_32x32x16_bf16 v[64:79], v[142:145], v[134:137], v[64:79]
	s_waitcnt lgkmcnt(7)
	v_mfma_f32_32x32x16_bf16 v[48:63], v[146:149], v[130:133], v[48:63]
	v_mfma_f32_32x32x16_bf16 v[32:47], v[146:149], v[134:137], v[32:47]
	s_waitcnt lgkmcnt(6)
	v_mfma_f32_32x32x16_bf16 v[16:31], v[150:153], v[130:133], v[16:31]
	v_mfma_f32_32x32x16_bf16 v[0:15], v[150:153], v[134:137], v[0:15]
	v_add_u32_e32 v134, v197, v178
	v_add_u32_e32 v150, v198, v178
	ds_read_b128 v[130:133], v134 offset:16384
	ds_read_b128 v[134:137], v134 offset:18432
	ds_read_b128 v[138:141], v150
	ds_read_b128 v[142:145], v150 offset:2048
	ds_read_b128 v[146:149], v150 offset:4096
	ds_read_b128 v[150:153], v150 offset:6144
	s_waitcnt lgkmcnt(9)
	v_mfma_f32_32x32x16_bf16 v[112:127], v[206:209], v[170:173], v[112:127]
	v_mfma_f32_32x32x16_bf16 v[96:111], v[206:209], v[202:205], v[96:111]
	s_waitcnt lgkmcnt(8)
	v_mfma_f32_32x32x16_bf16 v[80:95], v[210:213], v[170:173], v[80:95]
	v_mfma_f32_32x32x16_bf16 v[64:79], v[210:213], v[202:205], v[64:79]
	s_waitcnt lgkmcnt(7)
	v_mfma_f32_32x32x16_bf16 v[48:63], v[214:217], v[170:173], v[48:63]
	v_mfma_f32_32x32x16_bf16 v[32:47], v[214:217], v[202:205], v[32:47]
	s_waitcnt lgkmcnt(6)
	v_mfma_f32_32x32x16_bf16 v[16:31], v[224:227], v[170:173], v[16:31]
	s_movk_i32 s7, 0x1600
	v_mfma_f32_32x32x16_bf16 v[0:15], v[224:227], v[202:205], v[0:15]
	s_waitcnt lgkmcnt(3)
	v_mfma_f32_32x32x16_bf16 v[112:127], v[138:141], v[130:133], v[112:127]
	v_mfma_f32_32x32x16_bf16 v[96:111], v[138:141], v[134:137], v[96:111]
	s_nop 10
	v_cvt_pk_bf16_f32 v112, v112, s0
	s_waitcnt lgkmcnt(2)
	v_mfma_f32_32x32x16_bf16 v[80:95], v[142:145], v[130:133], v[80:95]
	v_cvt_pk_bf16_f32 v96, v96, s0
	v_cvt_pk_bf16_f32 v98, v98, s0
	s_waitcnt lgkmcnt(1)
	v_mfma_f32_32x32x16_bf16 v[48:63], v[146:149], v[130:133], v[48:63]
	s_nop 7
	v_cvt_pk_bf16_f32 v80, v80, s0
	s_waitcnt lgkmcnt(0)
	v_mfma_f32_32x32x16_bf16 v[16:31], v[150:153], v[130:133], v[16:31]
	v_add_u32_e32 v132, s3, v128
	v_or_b32_e32 v130, s4, v174
	v_ashrrev_i32_e32 v131, 31, v130
	v_lshl_add_u64 v[130:131], v[130:131], 1, v[158:159]
	v_cvt_pk_bf16_f32 v48, v48, s0
	v_readlane_b32 s3, v252, 7
	s_add_i32 s6, s6, s3
	v_mfma_f32_32x32x16_bf16 v[64:79], v[142:145], v[134:137], v[64:79]
	s_nop 3
	v_cvt_pk_bf16_f32 v16, v16, s0
	v_mfma_f32_32x32x16_bf16 v[32:47], v[146:149], v[134:137], v[32:47]
	s_nop 5
	v_cvt_pk_bf16_f32 v64, v64, s0
	v_cvt_pk_bf16_f32 v66, v66, s0
	v_mfma_f32_32x32x16_bf16 v[0:15], v[150:153], v[134:137], v[0:15]
	v_or_b32_e32 v134, v132, v181
	v_ashrrev_i32_e32 v135, 31, v134
	v_lshlrev_b64 v[134:135], 11, v[134:135]
	v_lshl_add_u64 v[134:135], v[130:131], 0, v[134:135]
	global_store_short v[134:135], v112, off
	global_store_short v[134:135], v96, off offset:64
	v_or_b32_e32 v134, v132, v182
	v_ashrrev_i32_e32 v135, 31, v134
	v_lshlrev_b64 v[134:135], 11, v[134:135]
	v_lshl_add_u64 v[134:135], v[130:131], 0, v[134:135]
	v_cvt_pk_bf16_f32 v96, v113, s0
	global_store_short v[134:135], v96, off
	v_cvt_pk_bf16_f32 v96, v97, s0
	global_store_short v[134:135], v96, off offset:64
	v_or_b32_e32 v96, v132, v183
	v_ashrrev_i32_e32 v97, 31, v96
	v_lshlrev_b64 v[96:97], 11, v[96:97]
	v_lshl_add_u64 v[96:97], v[130:131], 0, v[96:97]
	v_cvt_pk_bf16_f32 v112, v114, s0
	global_store_short v[96:97], v112, off
	global_store_short v[96:97], v98, off offset:64
	v_or_b32_e32 v96, v132, v184
	v_ashrrev_i32_e32 v97, 31, v96
	v_lshlrev_b64 v[96:97], 11, v[96:97]
	v_lshl_add_u64 v[96:97], v[130:131], 0, v[96:97]
	v_cvt_pk_bf16_f32 v98, v115, s0
	global_store_short v[96:97], v98, off
	v_cvt_pk_bf16_f32 v98, v99, s0
	global_store_short v[96:97], v98, off offset:64
	v_or_b32_e32 v96, v132, v185
	v_ashrrev_i32_e32 v97, 31, v96
	v_lshlrev_b64 v[96:97], 11, v[96:97]
	v_lshl_add_u64 v[96:97], v[130:131], 0, v[96:97]
	v_cvt_pk_bf16_f32 v98, v116, s0
	global_store_short v[96:97], v98, off
	v_cvt_pk_bf16_f32 v98, v100, s0
	global_store_short v[96:97], v98, off offset:64
	v_or_b32_e32 v96, v132, v186
	v_ashrrev_i32_e32 v97, 31, v96
	v_lshlrev_b64 v[96:97], 11, v[96:97]
	v_lshl_add_u64 v[96:97], v[130:131], 0, v[96:97]
	v_cvt_pk_bf16_f32 v98, v117, s0
	global_store_short v[96:97], v98, off
	v_cvt_pk_bf16_f32 v98, v101, s0
	global_store_short v[96:97], v98, off offset:64
	v_or_b32_e32 v96, v132, v187
	v_ashrrev_i32_e32 v97, 31, v96
	v_lshlrev_b64 v[96:97], 11, v[96:97]
	v_lshl_add_u64 v[96:97], v[130:131], 0, v[96:97]
	v_cvt_pk_bf16_f32 v98, v118, s0
	global_store_short v[96:97], v98, off
	v_cvt_pk_bf16_f32 v98, v102, s0
	global_store_short v[96:97], v98, off offset:64
	v_or_b32_e32 v96, v132, v188
	v_ashrrev_i32_e32 v97, 31, v96
	v_lshlrev_b64 v[96:97], 11, v[96:97]
	v_lshl_add_u64 v[96:97], v[130:131], 0, v[96:97]
	v_cvt_pk_bf16_f32 v98, v119, s0
	global_store_short v[96:97], v98, off
	v_cvt_pk_bf16_f32 v98, v103, s0
	global_store_short v[96:97], v98, off offset:64
	v_or_b32_e32 v96, v132, v189
	v_ashrrev_i32_e32 v97, 31, v96
	v_lshlrev_b64 v[96:97], 11, v[96:97]
	v_lshl_add_u64 v[96:97], v[130:131], 0, v[96:97]
	v_cvt_pk_bf16_f32 v98, v120, s0
	global_store_short v[96:97], v98, off
	v_cvt_pk_bf16_f32 v98, v104, s0
	global_store_short v[96:97], v98, off offset:64
	v_or_b32_e32 v96, v132, v190
	v_ashrrev_i32_e32 v97, 31, v96
	v_lshlrev_b64 v[96:97], 11, v[96:97]
	v_lshl_add_u64 v[96:97], v[130:131], 0, v[96:97]
	v_cvt_pk_bf16_f32 v98, v121, s0
	global_store_short v[96:97], v98, off
	v_cvt_pk_bf16_f32 v98, v105, s0
	global_store_short v[96:97], v98, off offset:64
	v_or_b32_e32 v96, v132, v191
	v_ashrrev_i32_e32 v97, 31, v96
	v_lshlrev_b64 v[96:97], 11, v[96:97]
	v_lshl_add_u64 v[96:97], v[130:131], 0, v[96:97]
	v_cvt_pk_bf16_f32 v98, v122, s0
	global_store_short v[96:97], v98, off
	v_cvt_pk_bf16_f32 v98, v106, s0
	global_store_short v[96:97], v98, off offset:64
	v_or_b32_e32 v96, v132, v192
	v_ashrrev_i32_e32 v97, 31, v96
	v_lshlrev_b64 v[96:97], 11, v[96:97]
	v_lshl_add_u64 v[96:97], v[130:131], 0, v[96:97]
	v_cvt_pk_bf16_f32 v98, v123, s0
	global_store_short v[96:97], v98, off
	v_cvt_pk_bf16_f32 v98, v107, s0
	global_store_short v[96:97], v98, off offset:64
	v_or_b32_e32 v96, v132, v193
	v_ashrrev_i32_e32 v97, 31, v96
	v_lshlrev_b64 v[96:97], 11, v[96:97]
	v_lshl_add_u64 v[96:97], v[130:131], 0, v[96:97]
	v_cvt_pk_bf16_f32 v98, v124, s0
	global_store_short v[96:97], v98, off
	v_cvt_pk_bf16_f32 v98, v108, s0
	global_store_short v[96:97], v98, off offset:64
	v_or_b32_e32 v96, v132, v194
	v_ashrrev_i32_e32 v97, 31, v96
	v_lshlrev_b64 v[96:97], 11, v[96:97]
	v_lshl_add_u64 v[96:97], v[130:131], 0, v[96:97]
	v_cvt_pk_bf16_f32 v98, v125, s0
	global_store_short v[96:97], v98, off
	v_cvt_pk_bf16_f32 v98, v109, s0
	global_store_short v[96:97], v98, off offset:64
	v_or_b32_e32 v96, v132, v195
	v_ashrrev_i32_e32 v97, 31, v96
	v_lshlrev_b64 v[96:97], 11, v[96:97]
	v_lshl_add_u64 v[96:97], v[130:131], 0, v[96:97]
	v_cvt_pk_bf16_f32 v98, v126, s0
	global_store_short v[96:97], v98, off
	v_cvt_pk_bf16_f32 v98, v110, s0
	global_store_short v[96:97], v98, off offset:64
	v_or_b32_e32 v96, v132, v196
	v_ashrrev_i32_e32 v97, 31, v96
	v_lshlrev_b64 v[96:97], 11, v[96:97]
	v_lshl_add_u64 v[96:97], v[130:131], 0, v[96:97]
	v_cvt_pk_bf16_f32 v98, v127, s0
	global_store_short v[96:97], v98, off
	v_cvt_pk_bf16_f32 v98, v111, s0
	global_store_short v[96:97], v98, off offset:64
	v_or_b32_e32 v98, 32, v132
	v_or_b32_e32 v96, v98, v181
	v_ashrrev_i32_e32 v97, 31, v96
	v_lshlrev_b64 v[96:97], 11, v[96:97]
	v_lshl_add_u64 v[96:97], v[130:131], 0, v[96:97]
	global_store_short v[96:97], v80, off
	global_store_short v[96:97], v64, off offset:64
	v_or_b32_e32 v96, v98, v182
	v_ashrrev_i32_e32 v97, 31, v96
	v_lshlrev_b64 v[96:97], 11, v[96:97]
	v_lshl_add_u64 v[96:97], v[130:131], 0, v[96:97]
	v_cvt_pk_bf16_f32 v64, v81, s0
	global_store_short v[96:97], v64, off
	v_cvt_pk_bf16_f32 v64, v65, s0
	global_store_short v[96:97], v64, off offset:64
	v_or_b32_e32 v64, v98, v183
	v_ashrrev_i32_e32 v65, 31, v64
	v_lshlrev_b64 v[64:65], 11, v[64:65]
	v_lshl_add_u64 v[64:65], v[130:131], 0, v[64:65]
	v_cvt_pk_bf16_f32 v80, v82, s0
	global_store_short v[64:65], v80, off
	global_store_short v[64:65], v66, off offset:64
	v_or_b32_e32 v64, v98, v184
	v_ashrrev_i32_e32 v65, 31, v64
	v_lshlrev_b64 v[64:65], 11, v[64:65]
	v_lshl_add_u64 v[64:65], v[130:131], 0, v[64:65]
	v_cvt_pk_bf16_f32 v66, v83, s0
	global_store_short v[64:65], v66, off
	v_cvt_pk_bf16_f32 v66, v67, s0
	global_store_short v[64:65], v66, off offset:64
	v_or_b32_e32 v64, v98, v185
	v_ashrrev_i32_e32 v65, 31, v64
	v_lshlrev_b64 v[64:65], 11, v[64:65]
	v_lshl_add_u64 v[64:65], v[130:131], 0, v[64:65]
	v_cvt_pk_bf16_f32 v66, v84, s0
	global_store_short v[64:65], v66, off
	v_cvt_pk_bf16_f32 v66, v68, s0
	global_store_short v[64:65], v66, off offset:64
	v_or_b32_e32 v64, v98, v186
	v_ashrrev_i32_e32 v65, 31, v64
	v_lshlrev_b64 v[64:65], 11, v[64:65]
	v_lshl_add_u64 v[64:65], v[130:131], 0, v[64:65]
	v_cvt_pk_bf16_f32 v66, v85, s0
	global_store_short v[64:65], v66, off
	v_cvt_pk_bf16_f32 v66, v69, s0
	global_store_short v[64:65], v66, off offset:64
	v_or_b32_e32 v64, v98, v187
	v_ashrrev_i32_e32 v65, 31, v64
	v_lshlrev_b64 v[64:65], 11, v[64:65]
	v_lshl_add_u64 v[64:65], v[130:131], 0, v[64:65]
	v_cvt_pk_bf16_f32 v66, v86, s0
	global_store_short v[64:65], v66, off
	v_cvt_pk_bf16_f32 v66, v70, s0
	global_store_short v[64:65], v66, off offset:64
	v_or_b32_e32 v64, v98, v188
	v_ashrrev_i32_e32 v65, 31, v64
	v_lshlrev_b64 v[64:65], 11, v[64:65]
	v_lshl_add_u64 v[64:65], v[130:131], 0, v[64:65]
	v_cvt_pk_bf16_f32 v66, v87, s0
	global_store_short v[64:65], v66, off
	v_cvt_pk_bf16_f32 v66, v71, s0
	global_store_short v[64:65], v66, off offset:64
	v_or_b32_e32 v64, v98, v189
	v_ashrrev_i32_e32 v65, 31, v64
	v_lshlrev_b64 v[64:65], 11, v[64:65]
	v_lshl_add_u64 v[64:65], v[130:131], 0, v[64:65]
	v_cvt_pk_bf16_f32 v66, v88, s0
	global_store_short v[64:65], v66, off
	v_cvt_pk_bf16_f32 v66, v72, s0
	global_store_short v[64:65], v66, off offset:64
	v_or_b32_e32 v64, v98, v190
	v_ashrrev_i32_e32 v65, 31, v64
	v_lshlrev_b64 v[64:65], 11, v[64:65]
	v_lshl_add_u64 v[64:65], v[130:131], 0, v[64:65]
	v_cvt_pk_bf16_f32 v66, v89, s0
	global_store_short v[64:65], v66, off
	v_cvt_pk_bf16_f32 v66, v73, s0
	global_store_short v[64:65], v66, off offset:64
	v_or_b32_e32 v64, v98, v191
	v_ashrrev_i32_e32 v65, 31, v64
	v_lshlrev_b64 v[64:65], 11, v[64:65]
	v_lshl_add_u64 v[64:65], v[130:131], 0, v[64:65]
	v_cvt_pk_bf16_f32 v66, v90, s0
	global_store_short v[64:65], v66, off
	v_cvt_pk_bf16_f32 v66, v74, s0
	global_store_short v[64:65], v66, off offset:64
	v_or_b32_e32 v64, v98, v192
	v_ashrrev_i32_e32 v65, 31, v64
	v_lshlrev_b64 v[64:65], 11, v[64:65]
	v_lshl_add_u64 v[64:65], v[130:131], 0, v[64:65]
	v_cvt_pk_bf16_f32 v66, v91, s0
	global_store_short v[64:65], v66, off
	v_cvt_pk_bf16_f32 v66, v75, s0
	global_store_short v[64:65], v66, off offset:64
	v_or_b32_e32 v64, v98, v193
	v_ashrrev_i32_e32 v65, 31, v64
	v_lshlrev_b64 v[64:65], 11, v[64:65]
	v_lshl_add_u64 v[64:65], v[130:131], 0, v[64:65]
	v_cvt_pk_bf16_f32 v66, v92, s0
	global_store_short v[64:65], v66, off
	v_cvt_pk_bf16_f32 v66, v76, s0
	global_store_short v[64:65], v66, off offset:64
	v_or_b32_e32 v64, v98, v194
	v_ashrrev_i32_e32 v65, 31, v64
	v_lshlrev_b64 v[64:65], 11, v[64:65]
	v_lshl_add_u64 v[64:65], v[130:131], 0, v[64:65]
	v_cvt_pk_bf16_f32 v66, v93, s0
	global_store_short v[64:65], v66, off
	v_cvt_pk_bf16_f32 v66, v77, s0
	global_store_short v[64:65], v66, off offset:64
	v_or_b32_e32 v64, v98, v195
	v_ashrrev_i32_e32 v65, 31, v64
	v_lshlrev_b64 v[64:65], 11, v[64:65]
	v_lshl_add_u64 v[64:65], v[130:131], 0, v[64:65]
	v_cvt_pk_bf16_f32 v66, v94, s0
	global_store_short v[64:65], v66, off
	v_cvt_pk_bf16_f32 v66, v78, s0
	global_store_short v[64:65], v66, off offset:64
	v_or_b32_e32 v64, v98, v196
	v_ashrrev_i32_e32 v65, 31, v64
	v_lshlrev_b64 v[64:65], 11, v[64:65]
	v_lshl_add_u64 v[64:65], v[130:131], 0, v[64:65]
	v_cvt_pk_bf16_f32 v66, v95, s0
	global_store_short v[64:65], v66, off
	v_cvt_pk_bf16_f32 v66, v79, s0
	global_store_short v[64:65], v66, off offset:64
	v_or_b32_e32 v66, 64, v132
	v_or_b32_e32 v64, v66, v181
	v_ashrrev_i32_e32 v65, 31, v64
	v_lshlrev_b64 v[64:65], 11, v[64:65]
	v_lshl_add_u64 v[64:65], v[130:131], 0, v[64:65]
	v_cvt_pk_bf16_f32 v32, v32, s0
	global_store_short v[64:65], v48, off
	global_store_short v[64:65], v32, off offset:64
	v_or_b32_e32 v64, v66, v182
	v_ashrrev_i32_e32 v65, 31, v64
	v_lshlrev_b64 v[64:65], 11, v[64:65]
	v_lshl_add_u64 v[64:65], v[130:131], 0, v[64:65]
	v_cvt_pk_bf16_f32 v32, v49, s0
	global_store_short v[64:65], v32, off
	v_cvt_pk_bf16_f32 v32, v33, s0
	global_store_short v[64:65], v32, off offset:64
	v_or_b32_e32 v32, v66, v183
	v_ashrrev_i32_e32 v33, 31, v32
	v_lshlrev_b64 v[32:33], 11, v[32:33]
	v_lshl_add_u64 v[32:33], v[130:131], 0, v[32:33]
	v_cvt_pk_bf16_f32 v48, v50, s0
	v_cvt_pk_bf16_f32 v34, v34, s0
	global_store_short v[32:33], v48, off
	global_store_short v[32:33], v34, off offset:64
	v_or_b32_e32 v32, v66, v184
	v_ashrrev_i32_e32 v33, 31, v32
	v_lshlrev_b64 v[32:33], 11, v[32:33]
	v_lshl_add_u64 v[32:33], v[130:131], 0, v[32:33]
	v_cvt_pk_bf16_f32 v34, v51, s0
	global_store_short v[32:33], v34, off
	v_cvt_pk_bf16_f32 v34, v35, s0
	global_store_short v[32:33], v34, off offset:64
	v_or_b32_e32 v32, v66, v185
	v_ashrrev_i32_e32 v33, 31, v32
	v_lshlrev_b64 v[32:33], 11, v[32:33]
	v_lshl_add_u64 v[32:33], v[130:131], 0, v[32:33]
	v_cvt_pk_bf16_f32 v34, v52, s0
	global_store_short v[32:33], v34, off
	v_cvt_pk_bf16_f32 v34, v36, s0
	global_store_short v[32:33], v34, off offset:64
	v_or_b32_e32 v32, v66, v186
	v_ashrrev_i32_e32 v33, 31, v32
	v_lshlrev_b64 v[32:33], 11, v[32:33]
	v_lshl_add_u64 v[32:33], v[130:131], 0, v[32:33]
	v_cvt_pk_bf16_f32 v34, v53, s0
	global_store_short v[32:33], v34, off
	v_cvt_pk_bf16_f32 v34, v37, s0
	global_store_short v[32:33], v34, off offset:64
	v_or_b32_e32 v32, v66, v187
	v_ashrrev_i32_e32 v33, 31, v32
	v_lshlrev_b64 v[32:33], 11, v[32:33]
	v_lshl_add_u64 v[32:33], v[130:131], 0, v[32:33]
	v_cvt_pk_bf16_f32 v34, v54, s0
	global_store_short v[32:33], v34, off
	v_cvt_pk_bf16_f32 v34, v38, s0
	global_store_short v[32:33], v34, off offset:64
	v_or_b32_e32 v32, v66, v188
	v_ashrrev_i32_e32 v33, 31, v32
	v_lshlrev_b64 v[32:33], 11, v[32:33]
	v_lshl_add_u64 v[32:33], v[130:131], 0, v[32:33]
	v_cvt_pk_bf16_f32 v34, v55, s0
	global_store_short v[32:33], v34, off
	v_cvt_pk_bf16_f32 v34, v39, s0
	global_store_short v[32:33], v34, off offset:64
	v_or_b32_e32 v32, v66, v189
	v_ashrrev_i32_e32 v33, 31, v32
	v_lshlrev_b64 v[32:33], 11, v[32:33]
	v_lshl_add_u64 v[32:33], v[130:131], 0, v[32:33]
	v_cvt_pk_bf16_f32 v34, v56, s0
	global_store_short v[32:33], v34, off
	v_cvt_pk_bf16_f32 v34, v40, s0
	global_store_short v[32:33], v34, off offset:64
	v_or_b32_e32 v32, v66, v190
	v_ashrrev_i32_e32 v33, 31, v32
	v_lshlrev_b64 v[32:33], 11, v[32:33]
	v_lshl_add_u64 v[32:33], v[130:131], 0, v[32:33]
	v_cvt_pk_bf16_f32 v34, v57, s0
	global_store_short v[32:33], v34, off
	v_cvt_pk_bf16_f32 v34, v41, s0
	global_store_short v[32:33], v34, off offset:64
	v_or_b32_e32 v32, v66, v191
	v_ashrrev_i32_e32 v33, 31, v32
	v_lshlrev_b64 v[32:33], 11, v[32:33]
	v_lshl_add_u64 v[32:33], v[130:131], 0, v[32:33]
	v_cvt_pk_bf16_f32 v34, v58, s0
	global_store_short v[32:33], v34, off
	v_cvt_pk_bf16_f32 v34, v42, s0
	global_store_short v[32:33], v34, off offset:64
	v_or_b32_e32 v32, v66, v192
	v_ashrrev_i32_e32 v33, 31, v32
	v_lshlrev_b64 v[32:33], 11, v[32:33]
	v_lshl_add_u64 v[32:33], v[130:131], 0, v[32:33]
	v_cvt_pk_bf16_f32 v34, v59, s0
	global_store_short v[32:33], v34, off
	v_cvt_pk_bf16_f32 v34, v43, s0
	global_store_short v[32:33], v34, off offset:64
	v_or_b32_e32 v32, v66, v193
	v_ashrrev_i32_e32 v33, 31, v32
	v_lshlrev_b64 v[32:33], 11, v[32:33]
	v_lshl_add_u64 v[32:33], v[130:131], 0, v[32:33]
	v_cvt_pk_bf16_f32 v34, v60, s0
	global_store_short v[32:33], v34, off
	v_cvt_pk_bf16_f32 v34, v44, s0
	global_store_short v[32:33], v34, off offset:64
	v_or_b32_e32 v32, v66, v194
	v_ashrrev_i32_e32 v33, 31, v32
	v_lshlrev_b64 v[32:33], 11, v[32:33]
	v_lshl_add_u64 v[32:33], v[130:131], 0, v[32:33]
	v_cvt_pk_bf16_f32 v34, v61, s0
	global_store_short v[32:33], v34, off
	v_cvt_pk_bf16_f32 v34, v45, s0
	global_store_short v[32:33], v34, off offset:64
	v_or_b32_e32 v32, v66, v195
	v_ashrrev_i32_e32 v33, 31, v32
	v_lshlrev_b64 v[32:33], 11, v[32:33]
	v_lshl_add_u64 v[32:33], v[130:131], 0, v[32:33]
	v_cvt_pk_bf16_f32 v34, v62, s0
	global_store_short v[32:33], v34, off
	v_cvt_pk_bf16_f32 v34, v46, s0
	global_store_short v[32:33], v34, off offset:64
	v_or_b32_e32 v32, v66, v196
	v_ashrrev_i32_e32 v33, 31, v32
	v_lshlrev_b64 v[32:33], 11, v[32:33]
	v_lshl_add_u64 v[32:33], v[130:131], 0, v[32:33]
	v_cvt_pk_bf16_f32 v34, v63, s0
	global_store_short v[32:33], v34, off
	v_cvt_pk_bf16_f32 v34, v47, s0
	global_store_short v[32:33], v34, off offset:64
	v_or_b32_e32 v34, 0x60, v132
	v_or_b32_e32 v32, v34, v181
	v_ashrrev_i32_e32 v33, 31, v32
	v_lshlrev_b64 v[32:33], 11, v[32:33]
	v_lshl_add_u64 v[32:33], v[130:131], 0, v[32:33]
	v_cvt_pk_bf16_f32 v0, v0, s0
	global_store_short v[32:33], v16, off
	global_store_short v[32:33], v0, off offset:64
	v_or_b32_e32 v32, v34, v182
	v_ashrrev_i32_e32 v33, 31, v32
	v_lshlrev_b64 v[32:33], 11, v[32:33]
	v_lshl_add_u64 v[32:33], v[130:131], 0, v[32:33]
	v_cvt_pk_bf16_f32 v0, v17, s0
	global_store_short v[32:33], v0, off
	v_cvt_pk_bf16_f32 v0, v1, s0
	global_store_short v[32:33], v0, off offset:64
	v_or_b32_e32 v0, v34, v183
	v_ashrrev_i32_e32 v1, 31, v0
	v_lshlrev_b64 v[0:1], 11, v[0:1]
	v_lshl_add_u64 v[0:1], v[130:131], 0, v[0:1]
	v_cvt_pk_bf16_f32 v16, v18, s0
	v_cvt_pk_bf16_f32 v2, v2, s0
	global_store_short v[0:1], v16, off
	global_store_short v[0:1], v2, off offset:64
	v_or_b32_e32 v0, v34, v184
	v_ashrrev_i32_e32 v1, 31, v0
	v_lshlrev_b64 v[0:1], 11, v[0:1]
	v_lshl_add_u64 v[0:1], v[130:131], 0, v[0:1]
	v_cvt_pk_bf16_f32 v2, v19, s0
	global_store_short v[0:1], v2, off
	v_cvt_pk_bf16_f32 v2, v3, s0
	global_store_short v[0:1], v2, off offset:64
	v_or_b32_e32 v0, v34, v185
	v_ashrrev_i32_e32 v1, 31, v0
	v_lshlrev_b64 v[0:1], 11, v[0:1]
	v_lshl_add_u64 v[0:1], v[130:131], 0, v[0:1]
	v_cvt_pk_bf16_f32 v2, v20, s0
	global_store_short v[0:1], v2, off
	v_cvt_pk_bf16_f32 v2, v4, s0
	global_store_short v[0:1], v2, off offset:64
	v_or_b32_e32 v0, v34, v186
	v_ashrrev_i32_e32 v1, 31, v0
	v_lshlrev_b64 v[0:1], 11, v[0:1]
	v_lshl_add_u64 v[0:1], v[130:131], 0, v[0:1]
	v_cvt_pk_bf16_f32 v2, v21, s0
	global_store_short v[0:1], v2, off
	v_cvt_pk_bf16_f32 v2, v5, s0
	global_store_short v[0:1], v2, off offset:64
	v_or_b32_e32 v0, v34, v187
	v_ashrrev_i32_e32 v1, 31, v0
	v_lshlrev_b64 v[0:1], 11, v[0:1]
	v_lshl_add_u64 v[0:1], v[130:131], 0, v[0:1]
	v_cvt_pk_bf16_f32 v2, v22, s0
	global_store_short v[0:1], v2, off
	v_cvt_pk_bf16_f32 v2, v6, s0
	global_store_short v[0:1], v2, off offset:64
	v_or_b32_e32 v0, v34, v188
	v_ashrrev_i32_e32 v1, 31, v0
	v_lshlrev_b64 v[0:1], 11, v[0:1]
	v_lshl_add_u64 v[0:1], v[130:131], 0, v[0:1]
	v_cvt_pk_bf16_f32 v2, v23, s0
	global_store_short v[0:1], v2, off
	v_cvt_pk_bf16_f32 v2, v7, s0
	global_store_short v[0:1], v2, off offset:64
	v_or_b32_e32 v0, v34, v189
	v_ashrrev_i32_e32 v1, 31, v0
	v_lshlrev_b64 v[0:1], 11, v[0:1]
	v_lshl_add_u64 v[0:1], v[130:131], 0, v[0:1]
	v_cvt_pk_bf16_f32 v2, v24, s0
	global_store_short v[0:1], v2, off
	v_cvt_pk_bf16_f32 v2, v8, s0
	global_store_short v[0:1], v2, off offset:64
	v_or_b32_e32 v0, v34, v190
	v_ashrrev_i32_e32 v1, 31, v0
	v_lshlrev_b64 v[0:1], 11, v[0:1]
	v_lshl_add_u64 v[0:1], v[130:131], 0, v[0:1]
	v_cvt_pk_bf16_f32 v2, v25, s0
	global_store_short v[0:1], v2, off
	v_cvt_pk_bf16_f32 v2, v9, s0
	global_store_short v[0:1], v2, off offset:64
	v_or_b32_e32 v0, v34, v191
	v_ashrrev_i32_e32 v1, 31, v0
	v_lshlrev_b64 v[0:1], 11, v[0:1]
	v_lshl_add_u64 v[0:1], v[130:131], 0, v[0:1]
	v_cvt_pk_bf16_f32 v2, v26, s0
	global_store_short v[0:1], v2, off
	v_cvt_pk_bf16_f32 v2, v10, s0
	global_store_short v[0:1], v2, off offset:64
	v_or_b32_e32 v0, v34, v192
	v_ashrrev_i32_e32 v1, 31, v0
	v_lshlrev_b64 v[0:1], 11, v[0:1]
	v_lshl_add_u64 v[0:1], v[130:131], 0, v[0:1]
	v_cvt_pk_bf16_f32 v2, v27, s0
	global_store_short v[0:1], v2, off
	v_cvt_pk_bf16_f32 v2, v11, s0
	global_store_short v[0:1], v2, off offset:64
	v_or_b32_e32 v0, v34, v193
	v_ashrrev_i32_e32 v1, 31, v0
	v_lshlrev_b64 v[0:1], 11, v[0:1]
	v_lshl_add_u64 v[0:1], v[130:131], 0, v[0:1]
	v_cvt_pk_bf16_f32 v2, v28, s0
	global_store_short v[0:1], v2, off
	v_cvt_pk_bf16_f32 v2, v12, s0
	global_store_short v[0:1], v2, off offset:64
	v_or_b32_e32 v0, v34, v194
	v_ashrrev_i32_e32 v1, 31, v0
	v_lshlrev_b64 v[0:1], 11, v[0:1]
	v_lshl_add_u64 v[0:1], v[130:131], 0, v[0:1]
	v_cvt_pk_bf16_f32 v2, v29, s0
	global_store_short v[0:1], v2, off
	v_cvt_pk_bf16_f32 v2, v13, s0
	global_store_short v[0:1], v2, off offset:64
	v_or_b32_e32 v0, v34, v195
	v_ashrrev_i32_e32 v1, 31, v0
	v_lshlrev_b64 v[0:1], 11, v[0:1]
	v_lshl_add_u64 v[0:1], v[130:131], 0, v[0:1]
	v_cvt_pk_bf16_f32 v2, v30, s0
	global_store_short v[0:1], v2, off
	v_cvt_pk_bf16_f32 v2, v14, s0
	global_store_short v[0:1], v2, off offset:64
	v_or_b32_e32 v0, v34, v196
	v_ashrrev_i32_e32 v1, 31, v0
	v_lshlrev_b64 v[0:1], 11, v[0:1]
	v_lshl_add_u64 v[0:1], v[130:131], 0, v[0:1]
	v_cvt_pk_bf16_f32 v2, v31, s0
	global_store_short v[0:1], v2, off
	v_cvt_pk_bf16_f32 v2, v15, s0
	s_add_i32 s0, s0, s3
	v_readlane_b32 s3, v252, 8
	s_add_i32 s2, s2, s3
	s_cmp_gt_i32 s6, 31
	global_store_short v[0:1], v2, off offset:64
	s_cbranch_scc0 .LBB0_2550
